# rstd_table: unit M-tile lane table instead of per-row integer division, plus repeated-row skip; padding keeps every GEMM loop at its previous address modulo 256
# baseline (speedup 1.0000x reference)
.Lrstd_done_0:
.LBB0_567:
	s_or_b64 exec, exec, s[4:5]
	v_add_u32_e32 v2, 0x200, v8
	v_mov_b32_e32 v3, s95
	v_cmp_gt_i32_e64 s[4:5], s18, v2
	s_and_saveexec_b64 s[6:7], s[4:5]
	s_cbranch_execz .LBB0_571
	v_ashrrev_i32_e32 v7, 8, v2
	s_mov_b64 s[0:1], exec
	v_readfirstlane_b32 vcc_lo, v7
	s_nop 3
	v_readlane_b32 vcc_lo, v31, vcc_lo
	s_nop 1
	v_mov_b32_e32 v6, vcc_lo

.Lrstd_done_1:
.LBB0_571:
	s_or_b64 exec, exec, s[6:7]
	v_add_u32_e32 v7, 0x400, v8
	v_mov_b32_e32 v2, s95
	v_cmp_gt_i32_e64 s[0:1], s18, v7
	s_and_saveexec_b64 s[16:17], s[0:1]
	s_cbranch_execz .LBB0_577
	v_ashrrev_i32_e32 v2, 8, v7
	s_mov_b64 s[6:7], exec
	v_readfirstlane_b32 vcc_lo, v2
	s_nop 3
	v_readlane_b32 vcc_lo, v31, vcc_lo
	s_nop 1
	v_mov_b32_e32 v6, vcc_lo

.LBB0_581:
	s_nop 0
	s_nop 0
	s_nop 0
	s_nop 0
	s_nop 0
	s_nop 0
	s_nop 0
	s_nop 0
	s_nop 0
	s_nop 0
	s_nop 0
	s_nop 0
	s_nop 0
	s_nop 0
	s_nop 0
	s_nop 0
	s_nop 0
	s_nop 0
	s_nop 0
	s_nop 0
	s_nop 0
	s_nop 0
	s_nop 0
	s_nop 0
	s_nop 0
	s_nop 0
	s_nop 0
	s_nop 0
	s_nop 0
	s_nop 0
	s_nop 0
	s_nop 0
	s_nop 0
	s_nop 0
	s_nop 0
	s_nop 0
	s_nop 0
	s_nop 0
	s_nop 0
	s_nop 0
	s_nop 0
	s_nop 0
	s_nop 0
	s_nop 0
	s_nop 0
	s_nop 0
	s_nop 0
	s_nop 0
	s_nop 0
	s_nop 0
	s_nop 0
	s_nop 0
	s_nop 0
	s_nop 0
	s_nop 0
	s_nop 0
	s_nop 0
	s_nop 0
	s_cmp_lt_i32 s80, s94
	s_cselect_b64 s[2:3], -1, 0
	s_cmp_ge_i32 s80, s94
	v_readfirstlane_b32 s18, v166
	s_waitcnt vmcnt(0) lgkmcnt(0)
	s_barrier
	s_cbranch_scc1 .LBB0_583
	s_lshr_b32 s0, s81, 29
	s_add_i32 s0, s80, s0
	s_ashr_i32 s1, s0, 3
	s_and_b32 s0, s0, -8
	s_sub_i32 s0, s80, s0
	s_cmp_lt_i32 s0, 0
	s_cselect_b32 s4, s92, s57
	s_mul_i32 s0, s4, s0
	s_add_i32 s0, s0, s1
	s_abs_i32 s4, s0
	s_mul_hi_u32 s5, s4, s93
	s_mul_i32 s6, s5, s13
	s_sub_i32 s4, s4, s6
	s_ashr_i32 s1, s0, 31
	s_add_i32 s6, s5, 1
	s_sub_i32 s7, s4, s13
	s_cmp_ge_u32 s4, s13
	s_cselect_b32 s5, s6, s5
	s_cselect_b32 s4, s7, s4
	s_add_i32 s6, s5, 1
	s_cmp_ge_u32 s4, s13
	s_cselect_b32 s4, s6, s5
	s_xor_b32 s4, s4, s1
	s_sub_i32 s1, s4, s1
	s_lshl_b32 s4, s1, 3
	s_sub_i32 s5, 0x80, s4
	s_min_i32 s5, s5, 8
	s_abs_i32 s6, s5
	v_cvt_f32_u32_e32 v0, s6
	s_sub_i32 s16, 0, s6
	s_mul_i32 s1, s1, s13
	s_sub_i32 s0, s0, s1
	v_rcp_iflag_f32_e32 v0, v0
	s_abs_i32 s7, s0
	s_xor_b32 s1, s0, s5
	s_ashr_i32 s1, s1, 31
	v_mul_f32_e32 v0, 0x4f7ffffe, v0
	v_cvt_u32_f32_e32 v0, v0
	s_nop 0
	v_readfirstlane_b32 s17, v0
	s_mul_i32 s16, s16, s17
	s_mul_hi_u32 s16, s17, s16
	s_add_i32 s17, s17, s16
	s_mul_hi_u32 s16, s7, s17
	s_mul_i32 s17, s16, s6
	s_sub_i32 s7, s7, s17
	s_add_i32 s17, s16, 1
	s_sub_i32 s19, s7, s6
	s_cmp_ge_u32 s7, s6
	s_cselect_b32 s16, s17, s16
	s_cselect_b32 s7, s19, s7
	s_add_i32 s17, s16, 1
	s_cmp_ge_u32 s7, s6
	s_cselect_b32 s6, s17, s16
	s_xor_b32 s6, s6, s1
	s_sub_i32 s72, s6, s1
	s_mul_i32 s1, s72, s5
	s_sub_i32 s0, s0, s1
	s_add_i32 s0, s0, s4

.Lrstd_done_3:
.LBB0_937:
	s_or_b64 exec, exec, s[4:5]
	v_add_u32_e32 v2, 0x200, v8
	v_mov_b32_e32 v3, s95
	v_cmp_gt_i32_e64 s[0:1], s10, v2
	s_and_saveexec_b64 s[6:7], s[0:1]
	s_cbranch_execz .LBB0_941
	v_ashrrev_i32_e32 v7, 8, v2
	s_mov_b64 s[4:5], exec
	v_readfirstlane_b32 vcc_lo, v7
	s_nop 3
	v_readlane_b32 vcc_lo, v31, vcc_lo
	s_nop 1
	v_mov_b32_e32 v6, vcc_lo

.Lrstd_done_4:
.LBB0_941:
	s_or_b64 exec, exec, s[6:7]
	v_add_u32_e32 v7, 0x400, v8
	v_mov_b32_e32 v2, s95
	v_cmp_gt_i32_e64 s[4:5], s10, v7
	s_and_saveexec_b64 s[8:9], s[4:5]
	s_cbranch_execz .LBB0_947
	v_ashrrev_i32_e32 v2, 8, v7
	s_mov_b64 s[6:7], exec
	v_readfirstlane_b32 vcc_lo, v2
	s_nop 3
	v_readlane_b32 vcc_lo, v31, vcc_lo
	s_nop 1
	v_mov_b32_e32 v6, vcc_lo

.LBB0_951:
	s_nop 0
	s_nop 0
	s_nop 0
	s_nop 0
	s_nop 0
	s_nop 0
	s_nop 0
	s_nop 0
	s_nop 0
	s_nop 0
	s_nop 0
	s_nop 0
	s_nop 0
	s_nop 0
	s_nop 0
	s_nop 0
	s_nop 0
	s_nop 0
	s_nop 0
	s_nop 0
	s_nop 0
	s_nop 0
	s_nop 0
	s_nop 0
	s_nop 0
	s_nop 0
	s_nop 0
	s_cmpk_gt_i32 s80, 0xaff
	v_readfirstlane_b32 s3, v166
	s_waitcnt vmcnt(0) lgkmcnt(0)
	s_barrier
	s_cbranch_scc1 .LBB0_967
	v_lshlrev_b32_e32 v0, 4, v166
	v_add_u32_e32 v2, 0x2000, v0
	v_ashrrev_i32_e32 v3, 31, v2
	v_lshrrev_b32_e32 v3, 22, v3
	v_add_u32_e32 v3, v2, v3
	v_ashrrev_i32_e32 v10, 10, v3
	s_mov_b32 s0, s18
	s_ashr_i32 s5, s3, 6
	v_mul_i32_i24_e32 v3, 0x400, v10
	s_ashr_i32 s4, s3, 8
	s_lshl_b32 s18, s5, 10
	s_mov_b32 s8, s0
	s_and_b32 s0, s0, 1
	v_sub_u32_e32 v2, v2, v3
	s_add_u32 s1, s58, 0x1b800000
	v_lshrrev_b32_e32 v3, 4, v2
	s_addc_u32 s2, s59, 0
	v_bitop3_b32 v2, v3, v2, 32 bitop3:0x6c
	s_cmp_eq_u32 s0, 0
	v_readlane_b32 s6, v254, 21
	v_ashrrev_i32_e32 v3, 31, v2
	v_readlane_b32 s7, v254, 22
	s_cselect_b32 s29, s6, s1
	s_mul_i32 s1, s8, 0xb00000
	v_lshrrev_b32_e32 v3, 26, v3
	s_cselect_b32 s19, s7, s2
	s_mul_hi_u32 s0, s8, 0xb00000
	s_add_u32 s1, s58, s1
	v_add_u32_e32 v3, v2, v3
	v_lshlrev_b32_e32 v4, 3, v10
	s_addc_u32 s0, s59, s0
	v_ashrrev_i32_e32 v11, 6, v3
	v_and_b32_e32 v4, -16, v4
	s_add_u32 s30, s1, 0x100000
	v_add_u32_e32 v4, v11, v4
	s_addc_u32 s31, s0, 0
	v_and_b32_e32 v5, 3, v11
	s_mov_b32 s0, 0x1fffe0
	v_lshrrev_b32_e32 v6, 2, v4
	v_lshlrev_b32_e32 v7, 1, v4
	v_and_b32_e32 v3, 0xc0, v3
	v_and_or_b32 v5, v4, s0, v5
	v_and_b32_e32 v6, 4, v6
	v_and_b32_e32 v7, 24, v7
	v_sub_u32_e32 v2, v2, v3
	v_or3_b32 v5, v5, v6, v7
	v_lshlrev_b32_e32 v6, 5, v10
	v_ashrrev_i16_sdwa v2, v219, sext(v2) dst_sel:DWORD dst_unused:UNUSED_PAD src0_sel:DWORD src1_sel:BYTE_0
	v_and_b32_e32 v6, 32, v6
	v_bfe_i32 v12, v2, 0, 16
	v_add_lshl_u32 v2, v6, v12, 1
	v_lshl_add_u32 v130, v5, 11, v2
	v_lshl_add_u32 v132, v4, 11, v2
	v_bfe_i32 v2, v166, 27, 1
	v_lshrrev_b32_e32 v2, 22, v2
	v_add_u32_e32 v2, v0, v2
	v_and_b32_e32 v2, 0xfffffc00, v2
	v_sub_u32_e32 v0, v0, v2
	v_lshrrev_b32_e32 v2, 4, v0
	v_ashrrev_i32_e32 v3, 31, v166
	v_bitop3_b32 v0, v2, v0, 32 bitop3:0x6c
	v_lshrrev_b32_e32 v3, 26, v3
	v_ashrrev_i32_e32 v2, 31, v0
	v_add_u32_e32 v3, v166, v3
	v_lshrrev_b32_e32 v2, 26, v2
	v_ashrrev_i32_e32 v14, 6, v3
	v_add_u32_e32 v2, v0, v2
	v_lshlrev_b32_e32 v3, 3, v14
	v_ashrrev_i32_e32 v13, 6, v2
	v_and_b32_e32 v3, -16, v3
	v_add_u32_e32 v3, v13, v3
	v_and_b32_e32 v4, 3, v13
	v_and_or_b32 v4, v3, s0, v4
	s_lshr_b32 s0, s81, 29
	s_add_i32 s0, s80, s0
	s_ashr_i32 s1, s0, 3
	s_and_b32 s0, s0, -8
	s_sub_i32 s0, s80, s0
	s_cmp_lt_i32 s0, 0
	s_movk_i32 s2, 0x161
	s_cselect_b32 s2, s2, 0x160
	s_mul_i32 s0, s0, s2
	s_add_i32 s0, s0, s1
	s_mul_hi_i32 s1, s0, 0x2e8ba2e9
	s_lshr_b32 s2, s1, 31
	s_ashr_i32 s1, s1, 5
	s_add_i32 s1, s1, s2
	s_lshl_b32 s6, s1, 3
	s_mulk_i32 s1, 0xb0
	s_sub_i32 s0, s0, s1
	s_bfe_u32 s1, s0, 0x3001c
	s_add_i32 s1, s0, s1
	s_sext_i32_i16 s2, s1
	s_and_b32 s1, s1, 0xfff8
	s_sub_i32 s0, s0, s1
	s_sext_i32_i16 s0, s0
	v_lshrrev_b32_e32 v5, 2, v3
	v_lshlrev_b32_e32 v6, 1, v3
	v_and_b32_e32 v2, 0xc0, v2
	s_lshr_b32 s2, s2, 3
	s_add_i32 s8, s6, s0
	v_and_b32_e32 v5, 4, v5
	v_and_b32_e32 v6, 24, v6
	v_sub_u32_e32 v0, v0, v2
	s_ashr_i32 s9, s8, 31
	s_bfe_i64 s[6:7], s[2:3], 0x100000
	v_or3_b32 v4, v4, v5, v6
	v_lshlrev_b32_e32 v5, 5, v14
	v_ashrrev_i16_sdwa v0, v219, sext(v0) dst_sel:DWORD dst_unused:UNUSED_PAD src0_sel:DWORD src1_sel:BYTE_0
	s_lshl_b64 s[0:1], s[8:9], 19
	s_lshl_b64 s[6:7], s[6:7], 19
	v_and_b32_e32 v5, 32, v5
	v_bfe_i32 v15, v0, 0, 16
	s_add_u32 s20, s30, s6
	v_add_lshl_u32 v2, v5, v15, 1
	s_addc_u32 s21, s31, s7
	s_add_i32 s34, s18, 0
	v_lshl_add_u32 v0, v4, 11, v2
	s_add_i32 m0, s34, 0x10000
	v_lshl_add_u32 v134, v3, 11, v2
	global_load_lds_dwordx4 v0, s[20:21]
	s_add_i32 m0, s34, 0x12000
	s_add_u32 s6, s20, 0x40000
	global_load_lds_dwordx4 v130, s[20:21]
	s_addc_u32 s7, s21, 0
	s_add_i32 m0, s34, 0x14000
	v_mov_b32_e32 v131, v1
	global_load_lds_dwordx4 v0, s[6:7]
	s_add_i32 m0, s34, 0x16000
	s_add_u32 s24, s29, s0
	s_addc_u32 s25, s19, s1
	s_add_i32 s35, s34, 0x2000
	global_load_lds_dwordx4 v130, s[6:7]
	s_mov_b32 m0, s34
	s_add_u32 s0, s24, 0x40000
	global_load_lds_dwordx4 v134, s[24:25]
	s_mov_b32 m0, s35
	s_addc_u32 s1, s25, 0
	s_add_i32 s38, s34, 0x4000
	global_load_lds_dwordx4 v132, s[24:25]
	s_mov_b32 m0, s38
	s_add_i32 s39, s34, 0x6000
	global_load_lds_dwordx4 v134, s[0:1]
	s_mov_b32 m0, s39
	v_mov_b32_e32 v135, v1
	global_load_lds_dwordx4 v132, s[0:1]
	v_mov_b32_e32 v133, v1
	s_cmp_eq_u32 s4, 1
	s_mov_b32 s75, s64
	v_lshl_add_u64 v[8:9], s[20:21], 0, v[0:1]
	v_lshl_add_u64 v[6:7], s[20:21], 0, v[130:131]
	v_lshl_add_u64 v[2:3], s[24:25], 0, v[134:135]
	s_cselect_b64 s[0:1], -1, 0
	v_lshl_add_u64 v[4:5], s[24:25], 0, v[132:133]
	s_mov_b32 s101, s4
	s_lshl_b32 s5, s5, 5
	s_and_b32 s11, s5, 0x60
	s_add_i32 m0, s34, 0x18000
	v_lshl_add_u64 v[8:9], v[8:9], 0, s[22:23]
	s_lshl_b32 s10, s4, 13
	s_lshl_b32 s5, s11, 7
	global_load_lds_dwordx4 v[8:9], off
	v_lshl_add_u64 v[6:7], v[6:7], 0, s[22:23]
	s_add_i32 m0, s34, 0x1a000
	s_add_i32 s57, s34, 0x8000
	s_add_i32 s61, s34, 0xa000
	global_load_lds_dwordx4 v[6:7], off
	v_lshl_add_u64 v[2:3], v[2:3], 0, s[22:23]
	s_mov_b32 m0, s57
	s_add_u32 s6, s20, 0x40080
	global_load_lds_dwordx4 v[2:3], off
	v_lshl_add_u64 v[2:3], v[4:5], 0, s[22:23]
	s_mov_b32 m0, s61
	s_addc_u32 s7, s21, 0
	global_load_lds_dwordx4 v[2:3], off
	s_add_i32 m0, s34, 0x1c000
	v_lshl_add_u64 v[2:3], s[6:7], 0, v[0:1]
	global_load_lds_dwordx4 v[2:3], off
	v_lshl_add_u64 v[2:3], s[6:7], 0, v[130:131]
	s_add_i32 m0, s34, 0x1e000
	v_lshlrev_b32_e32 v6, 2, v166
	global_load_lds_dwordx4 v[2:3], off
	s_cmp_lg_u32 s101, 1
	s_cbranch_scc1 .LBB0_954
	s_barrier
